# v21: v18 plus the fourth conv-weight load of the FFN-up epilogue issued with the first batch (one load round trip fewer per tile)
# speedup vs baseline: 1.0009x; 1.0009x over previous
; DI float silu_f(float x) { return x * __builtin_amdgcn_rcpf(1.f + __builtin_amdgcn_exp2f(-LOG2E * x)); }
; DI float rstd_of(float ssq, float inv_n) { return 1.0f / sqrtf(ssq * inv_n + EPS); }
; DI float acc_get_i(const acc_t* base, unsigned idx, float inv_scale) { return (float)(*(const acc_t*)((const char*)base + idx * 8u)) * inv_scale; }
;     DI void operator()(const f32x4 (&acc)[2][2][4][2], const Unit& u, int wr, int wc, int fr, int fq) const {
;     ...
;             const int c4 = c8 + 4 * n;
;             const f32x4 w0 = *(const f32x4*)(cw + c4), w1 = *(const f32x4*)(cw + DFF + c4), w2 = *(const f32x4*)(cw + 2 * DFF + c4), cbv = *(const f32x4*)(cb + c4);
; #pragma unroll
;             for (int ai = 0; ai < 2; ++ai) {
;                 f32x4 pg = {0.f, 0.f, 0.f, 0.f};
; #pragma unroll
;                 for (int m = 0; m < 4; ++m) { const int row = u.pm * BM + ai * HALF + wr * 64 + m * 16 + fr;
;                     const float rs = rstd_of(acc_get_i(ssq, (unsigned)row, 1.0f / SSQ_SCALE), 1.0f / DM);
;                     const f32x4 g = acc[ai][0][m][n] * rs, up = acc[ai][1][m][n] * rs;
;                     f32x4 a;
; #pragma unroll
;                     for (int j = 0; j < 4; ++j) { const float s1 = __shfl(fr == 15 ? pg[j] : g[j], src1), s2 = __shfl(fr >= 14 ? pg[j] : g[j], src2);
;                         a[j] = silu_f(cbv[j] + w0[j] * s2 + w1[j] * s1 + w2[j] * g[j]) * up[j]; }
.LBB0_3093:
	s_lshl_b32 s15, s0, 8
	s_add_i32 s15, s15, s80
	v_or_b32_e32 v194, s15, v209
	v_lshlrev_b32_e32 v96, 3, v194
	v_lshlrev_b64 v[142:143], 2, v[176:177]
	v_lshl_add_u64 v[178:179], s[54:55], 0, v[142:143]
	v_lshl_add_u64 v[134:135], s[62:63], 0, v[142:143]
	v_lshl_add_u64 v[138:139], s[64:65], 0, v[142:143]
	v_lshl_add_u64 v[180:181], s[56:57], 0, v[142:143]
	global_load_dwordx4 v[130:133], v[178:179], off
	global_load_dwordx4 v[142:145], v[180:181], off
	v_mul_lo_u32 v218, v194, s90
	global_load_dwordx4 v[134:137], v[134:135], off
	global_load_dwordx4 v[138:141], v[138:139], off
	global_load_dwordx2 v[236:237], v96, s[48:49]
	global_load_dwordx2 v[238:239], v96, s[48:49] offset:128
	global_load_dwordx2 v[240:241], v96, s[48:49] offset:256
	global_load_dwordx2 v[242:243], v96, s[48:49] offset:384
	global_load_dwordx2 v[246:247], v96, s[48:49] offset:1024
	global_load_dwordx2 v[250:251], v96, s[48:49] offset:1152
	global_load_dwordx2 v[146:147], v96, s[48:49] offset:1280
	global_load_dwordx2 v[148:149], v96, s[48:49] offset:1408
	s_waitcnt vmcnt(0)
	v_ffbh_u32_e32 v150, v237
	v_min_u32_e32 v150, 32, v150
	v_lshlrev_b64 v[236:237], v150, v[236:237]
	v_min_u32_e32 v236, 1, v236
	v_or_b32_e32 v236, v237, v236
	v_cvt_f32_u32_e32 v236, v236
	v_sub_u32_e32 v237, 32, v150
	v_ldexp_f32 v236, v236, v237
	v_mul_f32_e32 v236, 0x35800000, v236
	v_fmamk_f32 v236, v236, 0x3a800000, v222
	v_rsq_f32_e32 v237, v236
	s_nop 0
	v_mul_f32_e32 v150, v236, v237
	v_fma_f32 v150, -v150, v237, 1.0
	v_mul_f32_e32 v150, 0.5, v150
	v_fmac_f32_e32 v237, v150, v237
	v_ffbh_u32_e32 v150, v239
	v_min_u32_e32 v150, 32, v150
	v_lshlrev_b64 v[238:239], v150, v[238:239]
	v_min_u32_e32 v238, 1, v238
	v_or_b32_e32 v238, v239, v238
	v_cvt_f32_u32_e32 v238, v238
	v_sub_u32_e32 v239, 32, v150
	v_ldexp_f32 v238, v238, v239
	v_mul_f32_e32 v238, 0x35800000, v238
	v_fmamk_f32 v238, v238, 0x3a800000, v222
	v_rsq_f32_e32 v239, v238
	s_nop 0
	v_mul_f32_e32 v150, v238, v239
	v_fma_f32 v150, -v150, v239, 1.0
	v_mul_f32_e32 v150, 0.5, v150
	v_fmac_f32_e32 v239, v150, v239
	v_ffbh_u32_e32 v150, v241
	v_min_u32_e32 v150, 32, v150
	v_lshlrev_b64 v[240:241], v150, v[240:241]
	v_min_u32_e32 v240, 1, v240
	v_or_b32_e32 v240, v241, v240
	v_cvt_f32_u32_e32 v240, v240
	v_sub_u32_e32 v241, 32, v150
	v_ldexp_f32 v240, v240, v241
	v_mul_f32_e32 v240, 0x35800000, v240
	v_fmamk_f32 v240, v240, 0x3a800000, v222
	v_rsq_f32_e32 v241, v240
	s_nop 0
	v_mul_f32_e32 v150, v240, v241
	v_fma_f32 v150, -v150, v241, 1.0
	v_mul_f32_e32 v150, 0.5, v150
	v_fmac_f32_e32 v241, v150, v241
	v_ffbh_u32_e32 v150, v243
	v_min_u32_e32 v150, 32, v150
	v_lshlrev_b64 v[242:243], v150, v[242:243]
	v_min_u32_e32 v242, 1, v242
	v_or_b32_e32 v242, v243, v242
	v_cvt_f32_u32_e32 v242, v242
	v_sub_u32_e32 v243, 32, v150
	v_ldexp_f32 v242, v242, v243
	v_mul_f32_e32 v242, 0x35800000, v242
	v_fmamk_f32 v242, v242, 0x3a800000, v222
	v_rsq_f32_e32 v243, v242
	s_nop 0
	v_mul_f32_e32 v150, v242, v243
	v_fma_f32 v150, -v150, v243, 1.0
	v_mul_f32_e32 v150, 0.5, v150
	v_fmac_f32_e32 v243, v150, v243
	v_ffbh_u32_e32 v150, v247
	v_min_u32_e32 v150, 32, v150
	v_lshlrev_b64 v[246:247], v150, v[246:247]
	v_min_u32_e32 v246, 1, v246
	v_or_b32_e32 v246, v247, v246
	v_cvt_f32_u32_e32 v246, v246
	v_sub_u32_e32 v247, 32, v150
	v_ldexp_f32 v246, v246, v247
	v_mul_f32_e32 v246, 0x35800000, v246
	v_fmamk_f32 v246, v246, 0x3a800000, v222
	v_rsq_f32_e32 v247, v246
	s_nop 0
	v_mul_f32_e32 v150, v246, v247
	v_fma_f32 v150, -v150, v247, 1.0
	v_mul_f32_e32 v150, 0.5, v150
	v_fmac_f32_e32 v247, v150, v247
	v_ffbh_u32_e32 v150, v251
	v_min_u32_e32 v150, 32, v150
	v_lshlrev_b64 v[250:251], v150, v[250:251]
	v_min_u32_e32 v250, 1, v250
	v_or_b32_e32 v250, v251, v250
	v_cvt_f32_u32_e32 v250, v250
	v_sub_u32_e32 v251, 32, v150
	v_ldexp_f32 v250, v250, v251
	v_mul_f32_e32 v250, 0x35800000, v250
	v_fmamk_f32 v250, v250, 0x3a800000, v222
	v_rsq_f32_e32 v251, v250
	s_nop 0
	v_mul_f32_e32 v150, v250, v251
	v_fma_f32 v150, -v150, v251, 1.0
	v_mul_f32_e32 v150, 0.5, v150
	v_fmac_f32_e32 v251, v150, v251
	v_ffbh_u32_e32 v150, v147
	v_min_u32_e32 v150, 32, v150
	v_lshlrev_b64 v[146:147], v150, v[146:147]
	v_min_u32_e32 v146, 1, v146
	v_or_b32_e32 v146, v147, v146
	v_cvt_f32_u32_e32 v146, v146
	v_sub_u32_e32 v147, 32, v150
	v_ldexp_f32 v146, v146, v147
	v_mul_f32_e32 v146, 0x35800000, v146
	v_fmamk_f32 v146, v146, 0x3a800000, v222
	v_rsq_f32_e32 v147, v146
	s_nop 0
	v_mul_f32_e32 v150, v146, v147
	v_fma_f32 v150, -v150, v147, 1.0
	v_mul_f32_e32 v150, 0.5, v150
	v_fmac_f32_e32 v147, v150, v147
	v_ffbh_u32_e32 v150, v149
	v_min_u32_e32 v150, 32, v150
	v_lshlrev_b64 v[148:149], v150, v[148:149]
	v_min_u32_e32 v148, 1, v148
	v_or_b32_e32 v148, v149, v148
	v_cvt_f32_u32_e32 v148, v148
	v_sub_u32_e32 v149, 32, v150
	v_ldexp_f32 v148, v148, v149
	v_mul_f32_e32 v148, 0x35800000, v148
	v_fmamk_f32 v148, v148, 0x3a800000, v222
	v_rsq_f32_e32 v149, v148
	s_nop 0
	v_mul_f32_e32 v150, v148, v149
	v_fma_f32 v150, -v150, v149, 1.0
	v_mul_f32_e32 v150, 0.5, v150
	v_fmac_f32_e32 v149, v150, v149
	v_mov_b32_e32 v236, v237
	v_mov_b32_e32 v237, v239
	v_mov_b32_e32 v238, v241
	v_mov_b32_e32 v239, v243
	v_mov_b32_e32 v240, v247
	v_mov_b32_e32 v241, v251
	v_mov_b32_e32 v242, v147
	v_mov_b32_e32 v243, v149
	s_waitcnt vmcnt(0)
	v_mov_b32_e32 v148, v236
	v_pk_mul_f32 v[186:187], v[126:127], v[148:149] op_sel_hi:[1,0]
	v_pk_mul_f32 v[184:185], v[128:129], v[148:149] op_sel_hi:[1,0]
	v_mov_b32_e32 v188, 0
	v_mov_b32_dpp v188, v186 row_shr:1 row_mask:0xf bank_mask:0xf
	v_mov_b32_e32 v192, 0
	v_mov_b32_dpp v192, v186 row_shr:2 row_mask:0xf bank_mask:0xf
	v_mov_b32_e32 v189, 0
	v_mov_b32_dpp v189, v187 row_shr:1 row_mask:0xf bank_mask:0xf
	v_mov_b32_e32 v193, 0
	v_mov_b32_dpp v193, v187 row_shr:2 row_mask:0xf bank_mask:0xf
	v_mov_b32_e32 v182, 0
	v_mov_b32_dpp v182, v184 row_shr:1 row_mask:0xf bank_mask:0xf
	v_mov_b32_e32 v190, 0
	v_mov_b32_dpp v190, v184 row_shr:2 row_mask:0xf bank_mask:0xf
	v_mov_b32_e32 v183, 0
	v_mov_b32_dpp v183, v185 row_shr:1 row_mask:0xf bank_mask:0xf
	v_mov_b32_e32 v191, 0
	v_mov_b32_dpp v191, v185 row_shr:2 row_mask:0xf bank_mask:0xf
	v_pk_mul_f32 v[146:147], v[120:121], v[148:149] op_sel_hi:[1,0]
	v_pk_mul_f32 v[148:149], v[118:119], v[148:149] op_sel_hi:[1,0]
	s_and_saveexec_b64 s[0:1], s[40:41]
	s_xor_b64 s[0:1], exec, s[0:1]
	s_cbranch_execz .LBB0_3095
; DI unsigned pk2(float lo, float hi) { f32x2 v = {lo, hi}; bf16x2_t b = __builtin_convertvector(v, bf16x2_t); return __builtin_bit_cast(unsigned, b); }
; DI float silu_f(float x) { return x * __builtin_amdgcn_rcpf(1.f + __builtin_amdgcn_exp2f(-LOG2E * x)); }
; template <class T> DI T* boff(T* base, unsigned byte_off) { return (T*)((char*)base + byte_off); }
;     DI void operator()(const f32x4 (&acc)[2][2][4][2], const Unit& u, int wr, int wc, int fr, int fq) const {
;     ...
;                     for (int j = 0; j < 4; ++j) { const float s1 = __shfl(fr == 15 ? pg[j] : g[j], src1), s2 = __shfl(fr >= 14 ? pg[j] : g[j], src2);
;                         a[j] = silu_f(cbv[j] + w0[j] * s2 + w1[j] * s1 + w2[j] * g[j]) * up[j]; }
;                     u32x2 gw; gw.x = pk2(g[0], g[1]); gw.y = pk2(g[2], g[3]);
;                     if (m == 0 && fr < 2) {
;                         *boff((u32x2*)GS, (unsigned)(((row >> 6) * 4 + 2 + fr) * DFF + c4) * 2u) = gw;
;                         u32x2 uw; uw.x = pk2(up[0], up[1]); uw.y = pk2(up[2], up[3]); *boff((u32x2*)US, (unsigned)(((row >> 6) * 2 + fr) * DFF + c4) * 2u) = uw;
;                     } else { u32x2 w; w.x = pk2(a[0], a[1]); w.y = pk2(a[2], a[3]); *boff((u32x2*)A2, (unsigned)(row * DFF + c4) * 2u) = w; }
	s_waitcnt lgkmcnt(4)
	v_pk_fma_f32 v[150:151], v[130:131], v[192:193], v[142:143]
	s_nop 0
	v_pk_fma_f32 v[150:151], v[134:135], v[188:189], v[150:151]
	s_waitcnt lgkmcnt(0)
	v_pk_fma_f32 v[188:189], v[132:133], v[190:191], v[144:145]
	s_waitcnt vmcnt(0)
	v_pk_fma_f32 v[150:151], v[138:139], v[186:187], v[150:151]
	v_pk_fma_f32 v[182:183], v[136:137], v[182:183], v[188:189]
	v_mul_f32_e32 v152, 0xbfb8aa3b, v150
	v_mul_f32_e32 v153, 0xbfb8aa3b, v151
	v_pk_fma_f32 v[182:183], v[140:141], v[184:185], v[182:183]
	v_exp_f32_e32 v152, v152
	v_exp_f32_e32 v153, v153
	v_mul_f32_e32 v188, 0xbfb8aa3b, v182
	v_mul_f32_e32 v189, 0xbfb8aa3b, v183
	v_exp_f32_e32 v188, v188
	v_exp_f32_e32 v189, v189
	v_add_f32_e32 v152, 1.0, v152
	v_add_f32_e32 v153, 1.0, v153
	v_rcp_f32_e32 v152, v152
	v_rcp_f32_e32 v153, v153
	v_add_f32_e32 v188, 1.0, v188
	v_add_f32_e32 v189, 1.0, v189
	v_rcp_f32_e32 v188, v188
	v_rcp_f32_e32 v189, v189
	v_pk_mul_f32 v[150:151], v[150:151], v[152:153]
	s_nop 0
	v_pk_mul_f32 v[148:149], v[148:149], v[150:151]
	v_pk_mul_f32 v[150:151], v[182:183], v[188:189]
	v_cvt_pk_bf16_f32 v148, v148, v149
	v_pk_mul_f32 v[146:147], v[146:147], v[150:151]
	s_nop 0
	v_cvt_pk_bf16_f32 v149, v146, v147
	v_add_lshl_u32 v146, v218, v176, 1
	global_store_dwordx2 v146, v[148:149], s[46:47]
